# P3 head epilogue: second batch of row-scale loads issued one row group earlier (right after group 3 consumes its scale)
# baseline (speedup 1.0000x reference)
;     __device__ __forceinline__ void operator()(const f32x4 (&acc)[2][2][4][2], const pg8::Unit& u, int wr, int wc, int fr, int fq) const {
;     ...
;             for (int m = 0; m < 4; ++m) { const int row = row0 + ai * 128 + m * 16; const float rs = __builtin_amdgcn_rsqf(ss[row] * (1.f / DM) + EPS);
;                 f32x4 v[2][2]; float s = 0.f;
; #pragma unroll
;                 for (int bj = 0; bj < 2; ++bj)
; #pragma unroll
;                     for (int n = 0; n < 2; ++n) { v[bj][n] = acc[ai][bj][m][n] * rs; s += (v[bj][n][0] * v[bj][n][0] + v[bj][n][1] * v[bj][n][1]) + (v[bj][n][2] * v[bj][n][2] + v[bj][n][3] * v[bj][n][3]); }
;                 s += __shfl_xor(s, 16); s += __shfl_xor(s, 32);
;                 const float inv = (kind < 2) ? __builtin_amdgcn_rsqf(s * (1.f / 64.f) + EPS) : 1.f;
; #pragma unroll
;                 for (int bj = 0; bj < 2; ++bj)
; #pragma unroll
;                     for (int n = 0; n < 2; ++n) v[bj][n] = v[bj][n] * gv[bj][n] * inv;
;                 if (row < MPR) {
;                     const int b = row >> 11, sq = row & 2047, p = ((sq & (dil - 1)) << (11 - sh)) + (sq >> sh);
;                     bf16* dst = (bf16*)(wsb + boff) + ((size_t)(b * nh + idx) * 2048 + p) * 64;
.LBB0_651:
	s_or_b64 exec, exec, s[62:63]
	v_or_b32_e32 v176, 48, v166
	v_ashrrev_i32_e32 v177, 31, v176
	v_lshl_add_u64 v[150:151], v[176:177], 2, s[26:27]
	v_cmp_lt_i32_e32 vcc, s95, v176
	s_mov_b64 s[6:7], 0
	v_mov_b32_e32 v150, v197
	global_load_dword v194, v[170:171], off offset:512
	global_load_dword v195, v[170:171], off offset:576
	global_load_dword v196, v[170:171], off offset:640
	global_load_dword v197, v[170:171], off offset:704
	v_fmamk_f32 v150, v150, 0x3a800000, v236
	v_rsq_f32_e32 v164, v150
	s_nop 0
	v_pk_mul_f32 v[150:151], v[82:83], v[164:165] op_sel_hi:[1,0]
	v_pk_mul_f32 v[152:153], v[84:85], v[164:165] op_sel_hi:[1,0]
	v_pk_mul_f32 v[156:157], v[150:151], v[150:151]
	v_pk_mul_f32 v[154:155], v[152:153], v[152:153]
	s_nop 0
	v_pk_mov_b32 v[158:159], v[156:157], v[154:155] op_sel:[1,0]
	v_mov_b32_e32 v157, v155
	v_pk_add_f32 v[154:155], v[158:159], v[156:157]
	v_pk_mul_f32 v[156:157], v[80:81], v[164:165] op_sel_hi:[1,0]
	v_pk_add_f32 v[178:179], v[154:155], v[154:155] op_sel_hi:[0,1]
	v_pk_mul_f32 v[154:155], v[78:79], v[164:165] op_sel_hi:[1,0]
	v_pk_mul_f32 v[158:159], v[156:157], v[156:157]
	v_pk_mul_f32 v[160:161], v[154:155], v[154:155]
	s_nop 0
	v_pk_mov_b32 v[162:163], v[160:161], v[158:159] op_sel:[1,0]
	v_mov_b32_e32 v161, v159
	v_pk_add_f32 v[158:159], v[162:163], v[160:161]
	v_pk_mul_f32 v[160:161], v[74:75], v[164:165] op_sel_hi:[1,0]
	v_pk_add_f32 v[180:181], v[158:159], v[158:159] op_sel_hi:[0,1]
	v_pk_mul_f32 v[158:159], v[76:77], v[164:165] op_sel_hi:[1,0]
	v_mul_f32_e32 v162, v160, v160
	v_pk_fma_f32 v[182:183], v[160:161], v[160:161], v[162:163] op_sel_hi:[1,1,0]
	v_mul_f32_e32 v162, v158, v158
	v_pk_fma_f32 v[186:187], v[158:159], v[158:159], v[162:163] op_sel_hi:[1,1,0]
	v_pk_mul_f32 v[162:163], v[72:73], v[164:165] op_sel_hi:[1,0]
	v_pk_mul_f32 v[164:165], v[70:71], v[164:165] op_sel_hi:[1,0]
	v_mul_f32_e32 v178, v162, v162
	v_mul_f32_e32 v182, v164, v164
	v_mul_f32_e32 v186, v165, v165
	v_mul_f32_e32 v180, v163, v163
	v_pk_add_f32 v[182:183], v[182:183], v[186:187]
	v_pk_add_f32 v[178:179], v[178:179], v[180:181]
	s_nop 0
	v_pk_add_f32 v[178:179], v[182:183], v[178:179]
	s_nop 0
	v_add_f32_e32 v167, v178, v179
	ds_bpermute_b32 v173, v184, v167
	s_waitcnt lgkmcnt(0)
	v_add_f32_e32 v167, v167, v173
	ds_bpermute_b32 v173, v185, v167
	s_and_saveexec_b64 s[62:63], vcc
	s_xor_b64 s[62:63], exec, s[62:63]
	s_cbranch_execz .LBB0_659
	s_cmpk_lt_u32 s24, 0x8080
	s_cbranch_scc0 .LBB0_658
	v_add_u32_e32 v175, 0xffff8030, v166
	s_andn2_b64 vcc, exec, s[54:55]
	s_mov_b64 s[6:7], -1
	s_cbranch_vccnz .LBB0_655
	s_lshl_b64 s[6:7], s[58:59], 2
	s_add_u32 s64, s12, s6
	v_mov_b64_e32 v[176:177], s[60:61]
	s_addc_u32 s65, s13, s7
	v_mad_u64_u32 v[176:177], s[6:7], s70, v175, v[176:177]
	v_mov_b32_e32 v178, v177
	v_mad_u64_u32 v[178:179], s[6:7], s3, v175, v[178:179]
	v_mov_b32_e32 v177, v178
	v_lshl_add_u64 v[176:177], v[176:177], 1, v[168:169]
	v_lshlrev_b64 v[176:177], s50, v[176:177]
	v_lshl_add_u64 v[178:179], v[176:177], 0, s[18:19]
	s_mov_b64 s[6:7], 0

;     __device__ __forceinline__ void operator()(const f32x4 (&acc)[2][2][4][2], const pg8::Unit& u, int wr, int wc, int fr, int fq) const {
;     ...
;         for (int ai = 0; ai < 2; ++ai)
; #pragma unroll
;             for (int m = 0; m < 4; ++m) { const int row = row0 + ai * 128 + m * 16; const float rs = __builtin_amdgcn_rsqf(ss[row] * (1.f / DM) + EPS);
;                 f32x4 v[2][2]; float s = 0.f;
; #pragma unroll
;                 for (int bj = 0; bj < 2; ++bj)
; #pragma unroll
;                     for (int n = 0; n < 2; ++n) { v[bj][n] = acc[ai][bj][m][n] * rs; s += (v[bj][n][0] * v[bj][n][0] + v[bj][n][1] * v[bj][n][1]) + (v[bj][n][2] * v[bj][n][2] + v[bj][n][3] * v[bj][n][3]); }
;                 s += __shfl_xor(s, 16); s += __shfl_xor(s, 32);
;                 const float inv = (kind < 2) ? __builtin_amdgcn_rsqf(s * (1.f / 64.f) + EPS) : 1.f;
; #pragma unroll
;                 for (int bj = 0; bj < 2; ++bj)
; #pragma unroll
;                     for (int n = 0; n < 2; ++n) v[bj][n] = v[bj][n] * gv[bj][n] * inv;
;                 if (row < MPR) {
;                     const int b = row >> 11, sq = row & 2047, p = ((sq & (dil - 1)) << (11 - sh)) + (sq >> sh);
;                     bf16* dst = (bf16*)(wsb + boff) + ((size_t)(b * nh + idx) * 2048 + p) * 64;
.LBB0_665:
	s_or_b64 exec, exec, s[0:1]
	s_movk_i32 s0, 0x7f7f
	v_add_u32_e32 v167, 0x80, v166
	v_cmp_lt_i32_e32 vcc, s0, v166
	s_mov_b64 s[0:1], 0
	s_waitcnt vmcnt(0)
	v_mov_b32_e32 v150, v194
	v_fmamk_f32 v150, v150, 0x3a800000, v236
	v_rsq_f32_e32 v164, v150
	s_nop 0
	v_pk_mul_f32 v[150:151], v[66:67], v[164:165] op_sel_hi:[1,0]
	v_pk_mul_f32 v[152:153], v[68:69], v[164:165] op_sel_hi:[1,0]
	v_pk_mul_f32 v[156:157], v[150:151], v[150:151]
	v_pk_mul_f32 v[154:155], v[152:153], v[152:153]
	s_nop 0
	v_pk_mov_b32 v[158:159], v[156:157], v[154:155] op_sel:[1,0]
	v_mov_b32_e32 v157, v155
	v_pk_add_f32 v[154:155], v[158:159], v[156:157]
	v_pk_mul_f32 v[156:157], v[64:65], v[164:165] op_sel_hi:[1,0]
	v_pk_add_f32 v[176:177], v[154:155], v[154:155] op_sel_hi:[0,1]
	v_pk_mul_f32 v[154:155], v[62:63], v[164:165] op_sel_hi:[1,0]
	v_pk_mul_f32 v[158:159], v[156:157], v[156:157]
	v_pk_mul_f32 v[160:161], v[154:155], v[154:155]
	s_nop 0
	v_pk_mov_b32 v[162:163], v[160:161], v[158:159] op_sel:[1,0]
	v_mov_b32_e32 v161, v159
	v_pk_add_f32 v[158:159], v[162:163], v[160:161]
	v_pk_mul_f32 v[160:161], v[58:59], v[164:165] op_sel_hi:[1,0]
	v_pk_add_f32 v[178:179], v[158:159], v[158:159] op_sel_hi:[0,1]
	v_pk_mul_f32 v[158:159], v[60:61], v[164:165] op_sel_hi:[1,0]
	v_mul_f32_e32 v162, v160, v160
	v_pk_fma_f32 v[180:181], v[160:161], v[160:161], v[162:163] op_sel_hi:[1,1,0]
	v_mul_f32_e32 v162, v158, v158
	v_pk_fma_f32 v[182:183], v[158:159], v[158:159], v[162:163] op_sel_hi:[1,1,0]
	v_pk_mul_f32 v[162:163], v[56:57], v[164:165] op_sel_hi:[1,0]
	v_pk_mul_f32 v[164:165], v[54:55], v[164:165] op_sel_hi:[1,0]
	v_mul_f32_e32 v176, v162, v162
	v_mul_f32_e32 v180, v164, v164
	v_mul_f32_e32 v182, v165, v165
	v_mul_f32_e32 v178, v163, v163
	v_pk_add_f32 v[180:181], v[180:181], v[182:183]
	v_pk_add_f32 v[176:177], v[176:177], v[178:179]
	s_nop 0
	v_pk_add_f32 v[176:177], v[180:181], v[176:177]
	s_nop 0
	v_add_f32_e32 v173, v176, v177
	ds_bpermute_b32 v175, v184, v173
	s_waitcnt lgkmcnt(0)
	v_add_f32_e32 v173, v173, v175
	ds_bpermute_b32 v175, v185, v173
	s_and_saveexec_b64 s[4:5], vcc
	s_xor_b64 s[4:5], exec, s[4:5]
	s_cbranch_execz .LBB0_673
	s_mov_b32 s0, 0x8080
	v_cmp_gt_u32_e32 vcc, s0, v167
	s_mov_b64 s[62:63], 0
	s_and_saveexec_b64 s[0:1], vcc
	s_cbranch_execz .LBB0_672
	v_add_u32_e32 v176, 0xffff8080, v166
	s_andn2_b64 vcc, exec, s[54:55]
	s_mov_b64 s[62:63], -1
	s_cbranch_vccnz .LBB0_669
	v_mov_b64_e32 v[178:179], s[60:61]
	v_mad_u64_u32 v[178:179], s[24:25], s70, v176, v[178:179]
	v_mov_b32_e32 v180, v179
	v_mad_u64_u32 v[180:181], s[24:25], s3, v176, v[180:181]
	v_mov_b32_e32 v179, v180
	s_lshl_b64 s[6:7], s[58:59], 2
	v_lshl_add_u64 v[178:179], v[178:179], 1, v[168:169]
	s_add_u32 s6, s12, s6
	v_lshlrev_b64 v[178:179], s50, v[178:179]
	s_addc_u32 s7, s13, s7
	v_lshl_add_u64 v[180:181], v[178:179], 0, s[18:19]
	s_mov_b64 s[62:63], 0
